# RG-LRU fast paths: incremental 64-bit addressing for consecutive rows (offset:2048 pairs, +4096/+32768 via SGPR-pair constants) in tile-A flush and both prefetch copies
# speedup vs baseline: 1.0095x; 1.0075x over previous
; __device__ __forceinline__ void rglru_unit(const Params& p, const WS& ws, int j, int u, bool dry = false) {
;     ...
;   auto flush_y = [&]() {
;     if (ypend_t0 >= 0) {
; #pragma unroll
;       for (int i = 0; i < 8; ++i) {
;         const int t = ypend_t0 + 8 * ssg + i;
;         if (t < T_ && !dry) ws.GA[(size_t)(b * T_ + t) * 1024 + 128 * g + 32 * jq + sc] = ypend[i];
;       }
;     }
;   };
.LBB0_1376:
	s_cmp_lt_i32 s4, 0
	ds_write_b128 v106, v[20:23]
	ds_write_b128 v107, v[24:27]
	ds_write_b128 v109, v[28:31]
	ds_write_b128 v110, v[32:35]
	s_waitcnt lgkmcnt(0)
	s_barrier
	s_cbranch_scc1 .LBB0_1394
	s_cmpk_gt_i32 s4, 0x7d0
	s_cbranch_scc1 .Lrg_fslow1
	v_add_u32_e32 v13, s4, v83
	v_add_u32_e32 v52, s4, v69
	s_mov_b64 s[4:5], 0x1000
	v_ashrrev_i32_e32 v53, 31, v52
	v_lshlrev_b64 v[52:53], 11, v[52:53]
	v_lshl_add_u64 v[52:53], v[74:75], 0, v[52:53]
	global_store_short v[52:53], v58, off
	global_store_short v[52:53], v59, off offset:2048
	v_lshl_add_u64 v[52:53], v[52:53], 0, s[4:5]
	global_store_short v[52:53], v56, off
	global_store_short v[52:53], v57, off offset:2048
	v_lshl_add_u64 v[52:53], v[52:53], 0, s[4:5]
	global_store_short v[52:53], v54, off
	global_store_short v[52:53], v55, off offset:2048
	v_lshl_add_u64 v[52:53], v[52:53], 0, s[4:5]
	global_store_short v[52:53], v14, off
	global_store_short v[52:53], v15, off offset:2048
	s_branch .LBB0_1394

; __device__ __forceinline__ void rglru_unit(const Params& p, const WS& ws, int j, int u, bool dry = false) {
;     ...
;   auto prefetch = [&](int tile, u32x4 (&xin)[4], bf16_t (&gav)[8]) {
;     const int t0 = 64 * tile;
; #pragma unroll
;     for (int i = 0; i < 4; ++i) {
;       const int ci = tid + 256 * i; const int row = ci >> 4, ch = ci & 15; const int t = t0 + row;
;       xin[i] = (u32x4){0, 0, 0, 0};
;       if (t < T_) xin[i] = *(const u32x4*)(ws.XA + (size_t)(b * T_ + t) * 1024 + 128 * g + 8 * ch);
;     }
; #pragma unroll
;     for (int i = 0; i < 8; ++i) {
;       const int t = t0 + 8 * ssg + i;
;       gav[i] = 0;
;       if (t < T_) gav[i] = ws.GA[(size_t)(b * T_ + t) * 1024 + 128 * g + 32 * jq + sc];
;     }
;   };
.LBB0_1394:
	s_add_i32 s13, s7, -1
	s_cmp_gt_u32 s13, 30
	v_mov_b32_e32 v133, v127
	v_mov_b32_e32 v134, v128
	v_mov_b32_e32 v131, v123
	v_mov_b32_e32 v132, v124
	v_mov_b32_e32 v129, v121
	v_mov_b32_e32 v130, v122
	v_mov_b32_e32 v125, v119
	v_mov_b32_e32 v126, v120
	s_cbranch_scc1 .LBB0_1420
	s_cmpk_gt_i32 s6, 0x750
	s_cbranch_scc1 .Lrg_pslow1
	s_mov_b64 s[4:5], 0x1000
	s_mov_b64 s[52:53], 0x8000
	v_add_u32_e32 v14, s6, v118
	v_add_u32_e32 v14, 0x80, v14
	v_ashrrev_i32_e32 v15, 31, v14
	v_lshlrev_b64 v[14:15], 11, v[14:15]
	v_lshl_add_u64 v[14:15], v[76:77], 0, v[14:15]
	global_load_dwordx4 v[20:23], v[14:15], off
	v_lshl_add_u64 v[14:15], v[14:15], 0, s[52:53]
	global_load_dwordx4 v[24:27], v[14:15], off
	v_lshl_add_u64 v[14:15], v[14:15], 0, s[52:53]
	global_load_dwordx4 v[28:31], v[14:15], off
	v_lshl_add_u64 v[14:15], v[14:15], 0, s[52:53]
	global_load_dwordx4 v[32:35], v[14:15], off
	v_add_u32_e32 v14, s6, v69
	v_add_u32_e32 v14, 0x80, v14
	v_ashrrev_i32_e32 v15, 31, v14
	v_lshlrev_b64 v[14:15], 11, v[14:15]
	v_lshl_add_u64 v[14:15], v[74:75], 0, v[14:15]
	global_load_ushort v126, v[14:15], off
	global_load_ushort v125, v[14:15], off offset:2048
	v_lshl_add_u64 v[14:15], v[14:15], 0, s[4:5]
	global_load_ushort v130, v[14:15], off
	global_load_ushort v129, v[14:15], off offset:2048
	v_lshl_add_u64 v[14:15], v[14:15], 0, s[4:5]
	global_load_ushort v132, v[14:15], off
	global_load_ushort v131, v[14:15], off offset:2048
	v_lshl_add_u64 v[14:15], v[14:15], 0, s[4:5]
	global_load_ushort v134, v[14:15], off
	global_load_ushort v133, v[14:15], off offset:2048
	s_branch .LBB0_1420

; __device__ __forceinline__ void rglru_unit(const Params& p, const WS& ws, int j, int u, bool dry = false) {
;     ...
;   auto prefetch = [&](int tile, u32x4 (&xin)[4], bf16_t (&gav)[8]) {
;     const int t0 = 64 * tile;
; #pragma unroll
;     for (int i = 0; i < 4; ++i) {
;       const int ci = tid + 256 * i; const int row = ci >> 4, ch = ci & 15; const int t = t0 + row;
;       xin[i] = (u32x4){0, 0, 0, 0};
;       if (t < T_) xin[i] = *(const u32x4*)(ws.XA + (size_t)(b * T_ + t) * 1024 + 128 * g + 8 * ch);
;     }
; #pragma unroll
;     for (int i = 0; i < 8; ++i) {
;       const int t = t0 + 8 * ssg + i;
;       gav[i] = 0;
;       if (t < T_) gav[i] = ws.GA[(size_t)(b * T_ + t) * 1024 + 128 * g + 32 * jq + sc];
;     }
;   };
.Lrg_g2_skip:
	s_cmp_gt_u32 s7, 30
	v_mov_b32_e32 v151, v94
	v_mov_b32_e32 v152, v92
	v_mov_b32_e32 v149, v90
	v_mov_b32_e32 v150, v91
	v_mov_b32_e32 v147, v87
	v_mov_b32_e32 v243, v86
	v_mov_b32_e32 v146, v85
	v_mov_b32_e32 v148, v88
	s_cbranch_scc1 .LBB0_1505
	s_cmpk_gt_i32 s6, 0x710
	s_cbranch_scc1 .Lrg_pslow2
	s_mov_b64 s[4:5], 0x1000
	s_mov_b64 s[52:53], 0x8000
	v_add_u32_e32 v14, s6, v118
	v_add_u32_e32 v14, 0xc0, v14
	v_ashrrev_i32_e32 v15, 31, v14
	v_lshlrev_b64 v[14:15], 11, v[14:15]
	v_lshl_add_u64 v[14:15], v[76:77], 0, v[14:15]
	global_load_dwordx4 v[36:39], v[14:15], off
	v_lshl_add_u64 v[14:15], v[14:15], 0, s[52:53]
	global_load_dwordx4 v[40:43], v[14:15], off
	v_lshl_add_u64 v[14:15], v[14:15], 0, s[52:53]
	global_load_dwordx4 v[44:47], v[14:15], off
	v_lshl_add_u64 v[14:15], v[14:15], 0, s[52:53]
	global_load_dwordx4 v[48:51], v[14:15], off
	v_add_u32_e32 v14, 0xc0, v52
	v_ashrrev_i32_e32 v15, 31, v14
	v_lshlrev_b64 v[14:15], 11, v[14:15]
	v_lshl_add_u64 v[14:15], v[74:75], 0, v[14:15]
	global_load_ushort v243, v[14:15], off
	global_load_ushort v146, v[14:15], off offset:2048
	v_lshl_add_u64 v[14:15], v[14:15], 0, s[4:5]
	global_load_ushort v148, v[14:15], off
	global_load_ushort v147, v[14:15], off offset:2048
	v_lshl_add_u64 v[14:15], v[14:15], 0, s[4:5]
	global_load_ushort v150, v[14:15], off
	global_load_ushort v149, v[14:15], off offset:2048
	v_lshl_add_u64 v[14:15], v[14:15], 0, s[4:5]
	global_load_ushort v152, v[14:15], off
	global_load_ushort v151, v[14:15], off offset:2048
	s_branch .LBB0_1505
